# adds: P5 gate loads de-serialized + K-loop header vmcnt(0) dropped; P7 SwiGLU epilogue hand-written (SS2 prefetched before K loop, no register shuffles)
# speedup vs baseline: 1.0172x; 1.0021x over previous
; #define PG8_STAGE(bufoff, gbase, voff) do { _Pragma("unroll") for (int _i = 0; _i < 2; ++_i) \
;         __builtin_amdgcn_global_load_lds((const unsigned*)((const char*)(gbase) + (voff)[_i]), (LAS unsigned*)(lds + (bufoff) + ldsw + _i * 8192), 16, 0, 0); } while (0)
; #define PG8_LDA(dst, b, h) do { _Pragma("unroll") for (int m = 0; m < 4; ++m) _Pragma("unroll") for (int k = 0; k < 2; ++k) dst[m][k] = *(const LAS bf16x8*)(lds + PG8_SA(b, h) + aoff + m * 2048 + k * 1024); } while (0)
; #define PG8_LDB(dst, b, h) do { _Pragma("unroll") for (int n = 0; n < 2; ++n) _Pragma("unroll") for (int k = 0; k < 2; ++k) dst[n][k] = *(const LAS bf16x8*)(lds + PG8_SB(b, h) + boff + n * 2048 + k * 1024); } while (0)
; #define PG8_MMA(ai, bj, At, Bt) do { __builtin_amdgcn_s_setprio(1); _Pragma("unroll") for (int m = 0; m < 4; ++m) _Pragma("unroll") for (int n = 0; n < 2; ++n) _Pragma("unroll") for (int k = 0; k < 2; ++k) \
;         acc[ai][bj][m][n] = __builtin_amdgcn_mfma_f32_16x16x32_bf16(Bt[n][k], At[m][k], acc[ai][bj][m][n], 0, 0, 0); __builtin_amdgcn_s_setprio(0); } while (0)
; #define PG8_WAIT_V(n) asm volatile("s_waitcnt vmcnt(" #n ")" ::: "memory")
; #define PG8_WAIT_L(n) asm volatile("s_waitcnt lgkmcnt(" #n ")" ::: "memory")
; #define PG8_BAR __builtin_amdgcn_s_barrier()
; #define PG8_SCHED __builtin_amdgcn_sched_barrier(0)
; template <class Epi, class Sched, bool ALIGN_EPI>
; __device__ __forceinline__ void gemm_phase(LAS unsigned char* lds, const Gemm g, const Sched& S, const Epi& E) {
;     ...
;         for (int t = 0; t < nt; t += 2) {
;             const bool last = (t == nt - 2);
;             const char* a1 = cA + (size_t)(t + 1) * kstep;
;             const char* a2 = last ? nA : cA + (size_t)(t + 2) * kstep; const char* b2 = last ? nB : cB + (size_t)(t + 2) * kstep;
;             const char* a3 = a2 + kstep; const char* b3 = b2 + kstep;
;             PG8_LDB(B0, 0, 0); PG8_LDB(B1, 0, 1); PG8_SCHED; PG8_LDA(At, 0, 0); PG8_STAGE(PG8_SA(1, 1), a1 + hstepA, voffA);
;             PG8_WAIT_V(8); PG8_WAIT_L(0); PG8_BAR; PG8_MMA(0, 0, At, B0); PG8_MMA(0, 1, At, B1); PG8_BAR; PG8_SCHED;
;             PG8_LDA(At, 0, 1); PG8_STAGE(PG8_SB(0, 0), b2, voffB); PG8_STAGE(PG8_SB(0, 1), b2 + hstepB, voffB); PG8_STAGE(PG8_SA(0, 0), a2, voffA);
;             PG8_WAIT_V(8); PG8_WAIT_L(0); PG8_BAR; PG8_MMA(1, 0, At, B0); PG8_MMA(1, 1, At, B1); PG8_BAR; PG8_SCHED;
.LBB0_889:
	v_add_u32_e32 v0, s65, v219
	ds_read_b128 v[132:135], v0
	ds_read_b128 v[136:139], v0 offset:1024
	ds_read_b128 v[140:143], v0 offset:2048
	ds_read_b128 v[144:147], v0 offset:3072
	v_add_u32_e32 v0, s66, v219
	ds_read_b128 v[148:151], v0
	ds_read_b128 v[152:155], v0 offset:1024
	ds_read_b128 v[156:159], v0 offset:2048
	ds_read_b128 v[160:163], v0 offset:3072
	s_add_i32 s72, s52, 2
	s_add_u32 s73, s50, 0x80
	s_addc_u32 s53, s51, 0
	s_cmp_eq_u32 s63, s52
	s_cselect_b32 s52, s43, s73
	s_cselect_b32 s53, s7, s53
	s_cselect_b32 s75, s45, s71
	s_cselect_b32 s74, s69, s70
	v_lshl_add_u64 v[2:3], s[50:51], 0, v[204:205]
	s_add_i32 m0, s54, 0xc000
	ds_read_b128 v[164:167], v222
	ds_read_b128 v[168:171], v222 offset:1024
	ds_read_b128 v[172:175], v222 offset:2048
	ds_read_b128 v[176:179], v222 offset:3072
	ds_read_b128 v[180:183], v222 offset:4096
	ds_read_b128 v[184:187], v222 offset:5120
	ds_read_b128 v[188:191], v222 offset:6144
	ds_read_b128 v[192:195], v222 offset:7168
	global_load_lds_dwordx4 v[2:3], off
	v_lshl_add_u64 v[2:3], s[50:51], 0, v[206:207]
	s_add_i32 m0, s54, 0xe000
	s_nop 0
	global_load_lds_dwordx4 v[2:3], off
	s_waitcnt vmcnt(8)
	s_waitcnt lgkmcnt(0)
	s_barrier
	s_setprio 1
	s_waitcnt lgkmcnt(0)
	v_mfma_f32_16x16x32_bf16 v[128:131], v[132:135], v[164:167], v[128:131]
	v_mfma_f32_16x16x32_bf16 v[124:127], v[140:143], v[164:167], v[124:127]
	v_mfma_f32_16x16x32_bf16 v[120:123], v[132:135], v[172:175], v[120:123]
	v_mfma_f32_16x16x32_bf16 v[116:119], v[140:143], v[172:175], v[116:119]
	v_mfma_f32_16x16x32_bf16 v[112:115], v[132:135], v[180:183], v[112:115]
	v_mfma_f32_16x16x32_bf16 v[108:111], v[140:143], v[180:183], v[108:111]
	v_mfma_f32_16x16x32_bf16 v[104:107], v[132:135], v[188:191], v[104:107]
	v_mfma_f32_16x16x32_bf16 v[100:103], v[140:143], v[188:191], v[100:103]
	v_mfma_f32_16x16x32_bf16 v[128:131], v[136:139], v[168:171], v[128:131]
	v_mfma_f32_16x16x32_bf16 v[124:127], v[144:147], v[168:171], v[124:127]
	v_mfma_f32_16x16x32_bf16 v[120:123], v[136:139], v[176:179], v[120:123]
	v_mfma_f32_16x16x32_bf16 v[116:119], v[144:147], v[176:179], v[116:119]
	v_mfma_f32_16x16x32_bf16 v[112:115], v[136:139], v[184:187], v[112:115]
	v_mfma_f32_16x16x32_bf16 v[108:111], v[144:147], v[184:187], v[108:111]
	v_mfma_f32_16x16x32_bf16 v[104:107], v[136:139], v[192:195], v[104:107]
	v_mfma_f32_16x16x32_bf16 v[100:103], v[144:147], v[192:195], v[100:103]
	s_setprio 0
	s_setprio 1
	v_mfma_f32_16x16x32_bf16 v[96:99], v[148:151], v[164:167], v[96:99]
	v_mfma_f32_16x16x32_bf16 v[92:95], v[156:159], v[164:167], v[92:95]
	v_mfma_f32_16x16x32_bf16 v[88:91], v[148:151], v[172:175], v[88:91]
	v_mfma_f32_16x16x32_bf16 v[84:87], v[156:159], v[172:175], v[84:87]
	v_mfma_f32_16x16x32_bf16 v[80:83], v[148:151], v[180:183], v[80:83]
	v_mfma_f32_16x16x32_bf16 v[76:79], v[156:159], v[180:183], v[76:79]
	v_mfma_f32_16x16x32_bf16 v[72:75], v[148:151], v[188:191], v[72:75]
	v_mfma_f32_16x16x32_bf16 v[68:71], v[156:159], v[188:191], v[68:71]
	v_mfma_f32_16x16x32_bf16 v[96:99], v[152:155], v[168:171], v[96:99]
	v_mfma_f32_16x16x32_bf16 v[92:95], v[160:163], v[168:171], v[92:95]
	v_mfma_f32_16x16x32_bf16 v[88:91], v[152:155], v[176:179], v[88:91]
	v_mfma_f32_16x16x32_bf16 v[84:87], v[160:163], v[176:179], v[84:87]
	v_mfma_f32_16x16x32_bf16 v[80:83], v[152:155], v[184:187], v[80:83]
	v_mfma_f32_16x16x32_bf16 v[76:79], v[160:163], v[184:187], v[76:79]
	v_mfma_f32_16x16x32_bf16 v[72:75], v[152:155], v[192:195], v[72:75]
	v_mfma_f32_16x16x32_bf16 v[68:71], v[160:163], v[192:195], v[68:71]
	s_setprio 0
	s_barrier
	s_add_i32 s73, s65, s33
	v_lshl_add_u64 v[212:213], s[74:75], 0, v[198:199]
	s_mov_b32 m0, s73
	ds_read_b128 v[164:167], v222 offset:16384
	ds_read_b128 v[168:171], v222 offset:17408
	ds_read_b128 v[172:175], v222 offset:18432
	ds_read_b128 v[176:179], v222 offset:19456
	ds_read_b128 v[180:183], v222 offset:20480
	ds_read_b128 v[184:187], v222 offset:21504
	ds_read_b128 v[188:191], v222 offset:22528
	ds_read_b128 v[192:195], v222 offset:23552
	global_load_lds_dwordx4 v[212:213], off
	s_add_i32 m0, s73, 0x2000
	v_lshl_add_u64 v[214:215], s[74:75], 0, v[202:203]
	s_add_u32 s74, s74, s26
	s_addc_u32 s75, s75, s27
	s_add_i32 s73, s66, s33
	global_load_lds_dwordx4 v[214:215], off
	v_lshl_add_u64 v[216:217], s[74:75], 0, v[198:199]
	s_mov_b32 m0, s73
	v_lshl_add_u64 v[224:225], s[74:75], 0, v[202:203]
	global_load_lds_dwordx4 v[216:217], off
	s_add_i32 m0, s73, 0x2000
	v_lshl_add_u64 v[226:227], s[52:53], 0, v[196:197]
	global_load_lds_dwordx4 v[224:225], off
	s_mov_b32 m0, s54
	v_lshl_add_u64 v[228:229], s[52:53], 0, v[200:201]
	global_load_lds_dwordx4 v[226:227], off
	s_mov_b32 m0, s55
	s_nop 0
	global_load_lds_dwordx4 v[228:229], off
	s_waitcnt vmcnt(8)
	s_waitcnt lgkmcnt(0)
	s_barrier
; #define PG8_STAGE(bufoff, gbase, voff) do { _Pragma("unroll") for (int _i = 0; _i < 2; ++_i) \
;         __builtin_amdgcn_global_load_lds((const unsigned*)((const char*)(gbase) + (voff)[_i]), (LAS unsigned*)(lds + (bufoff) + ldsw + _i * 8192), 16, 0, 0); } while (0)
; #define PG8_LDA(dst, b, h) do { _Pragma("unroll") for (int m = 0; m < 4; ++m) _Pragma("unroll") for (int k = 0; k < 2; ++k) dst[m][k] = *(const LAS bf16x8*)(lds + PG8_SA(b, h) + aoff + m * 2048 + k * 1024); } while (0)
; #define PG8_LDB(dst, b, h) do { _Pragma("unroll") for (int n = 0; n < 2; ++n) _Pragma("unroll") for (int k = 0; k < 2; ++k) dst[n][k] = *(const LAS bf16x8*)(lds + PG8_SB(b, h) + boff + n * 2048 + k * 1024); } while (0)
; #define PG8_MMA(ai, bj, At, Bt) do { __builtin_amdgcn_s_setprio(1); _Pragma("unroll") for (int m = 0; m < 4; ++m) _Pragma("unroll") for (int n = 0; n < 2; ++n) _Pragma("unroll") for (int k = 0; k < 2; ++k) \
;         acc[ai][bj][m][n] = __builtin_amdgcn_mfma_f32_16x16x32_bf16(Bt[n][k], At[m][k], acc[ai][bj][m][n], 0, 0, 0); __builtin_amdgcn_s_setprio(0); } while (0)
; #define PG8_WAIT_V(n) asm volatile("s_waitcnt vmcnt(" #n ")" ::: "memory")
; #define PG8_WAIT_L(n) asm volatile("s_waitcnt lgkmcnt(" #n ")" ::: "memory")
; #define PG8_BAR __builtin_amdgcn_s_barrier()
; #define PG8_SCHED __builtin_amdgcn_sched_barrier(0)
; template <class Epi, class Sched, bool ALIGN_EPI>
; __device__ __forceinline__ void gemm_phase(LAS unsigned char* lds, const Gemm g, const Sched& S, const Epi& E) {
;     ...
;             PG8_WAIT_V(8); PG8_WAIT_L(0); PG8_BAR; PG8_MMA(1, 0, At, B0); PG8_MMA(1, 1, At, B1); PG8_BAR; PG8_SCHED;
;             PG8_LDB(B0, 1, 0); PG8_LDB(B1, 1, 1); PG8_SCHED; PG8_LDA(At, 1, 0); PG8_STAGE(PG8_SA(0, 1), a2 + hstepA, voffA);
;             PG8_WAIT_V(8); PG8_WAIT_L(0); PG8_BAR; PG8_MMA(0, 0, At, B0); PG8_MMA(0, 1, At, B1); PG8_BAR; PG8_SCHED;
	s_setprio 1
	s_waitcnt lgkmcnt(0)
	v_mfma_f32_16x16x32_bf16 v[64:67], v[132:135], v[164:167], v[64:67]
	v_mfma_f32_16x16x32_bf16 v[60:63], v[140:143], v[164:167], v[60:63]
	v_mfma_f32_16x16x32_bf16 v[56:59], v[132:135], v[172:175], v[56:59]
	v_mfma_f32_16x16x32_bf16 v[52:55], v[140:143], v[172:175], v[52:55]
	v_mfma_f32_16x16x32_bf16 v[48:51], v[132:135], v[180:183], v[48:51]
	v_mfma_f32_16x16x32_bf16 v[44:47], v[140:143], v[180:183], v[44:47]
	v_mfma_f32_16x16x32_bf16 v[40:43], v[132:135], v[188:191], v[40:43]
	v_mfma_f32_16x16x32_bf16 v[36:39], v[140:143], v[188:191], v[36:39]
	v_mfma_f32_16x16x32_bf16 v[64:67], v[136:139], v[168:171], v[64:67]
	v_mfma_f32_16x16x32_bf16 v[60:63], v[144:147], v[168:171], v[60:63]
	v_mfma_f32_16x16x32_bf16 v[56:59], v[136:139], v[176:179], v[56:59]
	v_mfma_f32_16x16x32_bf16 v[52:55], v[144:147], v[176:179], v[52:55]
	v_mfma_f32_16x16x32_bf16 v[48:51], v[136:139], v[184:187], v[48:51]
	v_mfma_f32_16x16x32_bf16 v[44:47], v[144:147], v[184:187], v[44:47]
	v_mfma_f32_16x16x32_bf16 v[40:43], v[136:139], v[192:195], v[40:43]
	v_mfma_f32_16x16x32_bf16 v[36:39], v[144:147], v[192:195], v[36:39]
	s_setprio 0
	s_setprio 1
	v_mfma_f32_16x16x32_bf16 v[32:35], v[148:151], v[164:167], v[32:35]
	v_mfma_f32_16x16x32_bf16 v[28:31], v[156:159], v[164:167], v[28:31]
	v_mfma_f32_16x16x32_bf16 v[24:27], v[148:151], v[172:175], v[24:27]
	v_mfma_f32_16x16x32_bf16 v[20:23], v[156:159], v[172:175], v[20:23]
	v_mfma_f32_16x16x32_bf16 v[16:19], v[148:151], v[180:183], v[16:19]
	v_mfma_f32_16x16x32_bf16 v[12:15], v[156:159], v[180:183], v[12:15]
	v_mfma_f32_16x16x32_bf16 v[8:11], v[148:151], v[188:191], v[8:11]
	v_mfma_f32_16x16x32_bf16 v[2:5], v[156:159], v[188:191], v[4:7]
	v_mfma_f32_16x16x32_bf16 v[32:35], v[152:155], v[168:171], v[32:35]
	v_mfma_f32_16x16x32_bf16 v[28:31], v[160:163], v[168:171], v[28:31]
	v_mfma_f32_16x16x32_bf16 v[24:27], v[152:155], v[176:179], v[24:27]
	v_mfma_f32_16x16x32_bf16 v[20:23], v[160:163], v[176:179], v[20:23]
	v_mfma_f32_16x16x32_bf16 v[16:19], v[152:155], v[184:187], v[16:19]
	v_mfma_f32_16x16x32_bf16 v[12:15], v[160:163], v[184:187], v[12:15]
	v_mfma_f32_16x16x32_bf16 v[8:11], v[152:155], v[192:195], v[8:11]
	v_mfma_f32_16x16x32_bf16 v[2:5], v[160:163], v[192:195], v[2:5]
	s_setprio 0
	s_barrier
	s_add_i32 s73, 0, 0x18000
	v_add_u32_e32 v0, s73, v219
	s_add_i32 s74, 0, 0x1c000
	ds_read_b128 v[132:135], v0
	ds_read_b128 v[136:139], v0 offset:1024
	ds_read_b128 v[140:143], v0 offset:2048
	ds_read_b128 v[144:147], v0 offset:3072
	v_add_u32_e32 v0, s74, v219
	ds_read_b128 v[148:151], v0
	ds_read_b128 v[152:155], v0 offset:1024
	ds_read_b128 v[156:159], v0 offset:2048
	ds_read_b128 v[160:163], v0 offset:3072
	s_add_u32 s52, s52, s24
	s_addc_u32 s53, s53, s25
	s_mov_b32 m0, s58
	v_lshl_add_u64 v[6:7], s[52:53], 0, v[196:197]
	ds_read_b128 v[164:167], v222 offset:32768
	ds_read_b128 v[168:171], v222 offset:33792
	ds_read_b128 v[172:175], v222 offset:34816
	ds_read_b128 v[176:179], v222 offset:35840
	ds_read_b128 v[180:183], v222 offset:36864
	ds_read_b128 v[184:187], v222 offset:37888
	ds_read_b128 v[188:191], v222 offset:38912
	ds_read_b128 v[192:195], v222 offset:39936
	global_load_lds_dwordx4 v[6:7], off
	v_lshl_add_u64 v[6:7], s[52:53], 0, v[200:201]
	s_mov_b32 m0, s59
	s_nop 0
	global_load_lds_dwordx4 v[6:7], off
	s_waitcnt vmcnt(8)
	s_waitcnt lgkmcnt(0)
	s_barrier
	s_setprio 1
	s_waitcnt lgkmcnt(0)
	v_mfma_f32_16x16x32_bf16 v[128:131], v[132:135], v[164:167], v[128:131]
	v_mfma_f32_16x16x32_bf16 v[124:127], v[140:143], v[164:167], v[124:127]
	v_mfma_f32_16x16x32_bf16 v[120:123], v[132:135], v[172:175], v[120:123]
	v_mfma_f32_16x16x32_bf16 v[116:119], v[140:143], v[172:175], v[116:119]
	v_mfma_f32_16x16x32_bf16 v[112:115], v[132:135], v[180:183], v[112:115]
	v_mfma_f32_16x16x32_bf16 v[108:111], v[140:143], v[180:183], v[108:111]
	v_mfma_f32_16x16x32_bf16 v[104:107], v[132:135], v[188:191], v[104:107]
	v_mfma_f32_16x16x32_bf16 v[100:103], v[140:143], v[188:191], v[100:103]
	v_mfma_f32_16x16x32_bf16 v[128:131], v[136:139], v[168:171], v[128:131]
	v_mfma_f32_16x16x32_bf16 v[124:127], v[144:147], v[168:171], v[124:127]
	v_mfma_f32_16x16x32_bf16 v[120:123], v[136:139], v[176:179], v[120:123]
	v_mfma_f32_16x16x32_bf16 v[116:119], v[144:147], v[176:179], v[116:119]
	v_mfma_f32_16x16x32_bf16 v[112:115], v[136:139], v[184:187], v[112:115]
	v_mfma_f32_16x16x32_bf16 v[108:111], v[144:147], v[184:187], v[108:111]
	v_mfma_f32_16x16x32_bf16 v[104:107], v[136:139], v[192:195], v[104:107]
	v_mfma_f32_16x16x32_bf16 v[100:103], v[144:147], v[192:195], v[100:103]
	s_setprio 0
	s_setprio 1
	v_mfma_f32_16x16x32_bf16 v[96:99], v[148:151], v[164:167], v[96:99]
	v_mfma_f32_16x16x32_bf16 v[92:95], v[156:159], v[164:167], v[92:95]
	v_mfma_f32_16x16x32_bf16 v[88:91], v[148:151], v[172:175], v[88:91]
	v_mfma_f32_16x16x32_bf16 v[84:87], v[156:159], v[172:175], v[84:87]
	v_mfma_f32_16x16x32_bf16 v[80:83], v[148:151], v[180:183], v[80:83]
	v_mfma_f32_16x16x32_bf16 v[76:79], v[156:159], v[180:183], v[76:79]
	v_mfma_f32_16x16x32_bf16 v[72:75], v[148:151], v[188:191], v[72:75]
	v_mfma_f32_16x16x32_bf16 v[68:71], v[156:159], v[188:191], v[68:71]
	v_mfma_f32_16x16x32_bf16 v[96:99], v[152:155], v[168:171], v[96:99]
	v_mfma_f32_16x16x32_bf16 v[92:95], v[160:163], v[168:171], v[92:95]
	v_mfma_f32_16x16x32_bf16 v[88:91], v[152:155], v[176:179], v[88:91]
	v_mfma_f32_16x16x32_bf16 v[84:87], v[160:163], v[176:179], v[84:87]
	v_mfma_f32_16x16x32_bf16 v[80:83], v[152:155], v[184:187], v[80:83]
	v_mfma_f32_16x16x32_bf16 v[76:79], v[160:163], v[184:187], v[76:79]
	v_mfma_f32_16x16x32_bf16 v[72:75], v[152:155], v[192:195], v[72:75]
	v_mfma_f32_16x16x32_bf16 v[68:71], v[160:163], v[192:195], v[68:71]
	s_setprio 0
	s_barrier
; #define PG8_STAGE(bufoff, gbase, voff) do { _Pragma("unroll") for (int _i = 0; _i < 2; ++_i) \
;         __builtin_amdgcn_global_load_lds((const unsigned*)((const char*)(gbase) + (voff)[_i]), (LAS unsigned*)(lds + (bufoff) + ldsw + _i * 8192), 16, 0, 0); } while (0)
; #define PG8_LDA(dst, b, h) do { _Pragma("unroll") for (int m = 0; m < 4; ++m) _Pragma("unroll") for (int k = 0; k < 2; ++k) dst[m][k] = *(const LAS bf16x8*)(lds + PG8_SA(b, h) + aoff + m * 2048 + k * 1024); } while (0)
; #define PG8_MMA(ai, bj, At, Bt) do { __builtin_amdgcn_s_setprio(1); _Pragma("unroll") for (int m = 0; m < 4; ++m) _Pragma("unroll") for (int n = 0; n < 2; ++n) _Pragma("unroll") for (int k = 0; k < 2; ++k) \
;         acc[ai][bj][m][n] = __builtin_amdgcn_mfma_f32_16x16x32_bf16(Bt[n][k], At[m][k], acc[ai][bj][m][n], 0, 0, 0); __builtin_amdgcn_s_setprio(0); } while (0)
; #define PG8_WAIT_V(n) asm volatile("s_waitcnt vmcnt(" #n ")" ::: "memory")
; #define PG8_WAIT_L(n) asm volatile("s_waitcnt lgkmcnt(" #n ")" ::: "memory")
; #define PG8_BAR __builtin_amdgcn_s_barrier()
; #define PG8_SCHED __builtin_amdgcn_sched_barrier(0)
; template <class Epi, class Sched, bool ALIGN_EPI>
; __device__ __forceinline__ void gemm_phase(LAS unsigned char* lds, const Gemm g, const Sched& S, const Epi& E) {
;     ...
;             PG8_LDA(At, 1, 1); PG8_STAGE(PG8_SB(1, 0), b3, voffB); PG8_STAGE(PG8_SB(1, 1), b3 + hstepB, voffB); PG8_STAGE(PG8_SA(1, 0), a3, voffA);
;             PG8_WAIT_V(8); PG8_WAIT_L(0); PG8_BAR; PG8_MMA(1, 0, At, B0); PG8_MMA(1, 1, At, B1); PG8_BAR; PG8_SCHED;
;         }
	s_add_i32 s52, s73, s33
	v_lshl_add_u64 v[6:7], v[212:213], 0, s[30:31]
	s_mov_b32 m0, s52
	ds_read_b128 v[164:167], v222 offset:49152
	ds_read_b128 v[168:171], v222 offset:50176
	ds_read_b128 v[172:175], v222 offset:51200
	ds_read_b128 v[176:179], v222 offset:52224
	ds_read_b128 v[180:183], v222 offset:53248
	ds_read_b128 v[184:187], v222 offset:54272
	ds_read_b128 v[188:191], v222 offset:55296
	ds_read_b128 v[192:195], v222 offset:56320
	global_load_lds_dwordx4 v[6:7], off
	v_lshl_add_u64 v[6:7], v[214:215], 0, s[30:31]
	s_add_i32 m0, s52, 0x2000
	s_add_i32 s52, s74, s33
	global_load_lds_dwordx4 v[6:7], off
	v_lshl_add_u64 v[6:7], v[216:217], 0, s[30:31]
	s_mov_b32 m0, s52
	s_nop 0
	global_load_lds_dwordx4 v[6:7], off
	v_lshl_add_u64 v[6:7], v[224:225], 0, s[30:31]
	s_add_i32 m0, s52, 0x2000
	s_nop 0
	global_load_lds_dwordx4 v[6:7], off
	v_lshl_add_u64 v[6:7], v[226:227], 0, s[30:31]
	s_mov_b32 m0, s60
	s_nop 0
	global_load_lds_dwordx4 v[6:7], off
	v_lshl_add_u64 v[6:7], v[228:229], 0, s[30:31]
	s_mov_b32 m0, s61
	s_nop 0
	global_load_lds_dwordx4 v[6:7], off
	s_waitcnt vmcnt(8)
	s_waitcnt lgkmcnt(0)
	s_barrier
	s_setprio 1
	s_waitcnt lgkmcnt(0)
	v_mfma_f32_16x16x32_bf16 v[64:67], v[132:135], v[164:167], v[64:67]
	v_mfma_f32_16x16x32_bf16 v[60:63], v[140:143], v[164:167], v[60:63]
	v_mfma_f32_16x16x32_bf16 v[56:59], v[132:135], v[172:175], v[56:59]
	v_mfma_f32_16x16x32_bf16 v[52:55], v[140:143], v[172:175], v[52:55]
	v_mfma_f32_16x16x32_bf16 v[48:51], v[132:135], v[180:183], v[48:51]
	v_mfma_f32_16x16x32_bf16 v[44:47], v[140:143], v[180:183], v[44:47]
	v_mfma_f32_16x16x32_bf16 v[40:43], v[132:135], v[188:191], v[40:43]
	v_mfma_f32_16x16x32_bf16 v[36:39], v[140:143], v[188:191], v[36:39]
	v_mfma_f32_16x16x32_bf16 v[64:67], v[136:139], v[168:171], v[64:67]
	v_mfma_f32_16x16x32_bf16 v[60:63], v[144:147], v[168:171], v[60:63]
	v_mfma_f32_16x16x32_bf16 v[56:59], v[136:139], v[176:179], v[56:59]
	v_mfma_f32_16x16x32_bf16 v[52:55], v[144:147], v[176:179], v[52:55]
	v_mfma_f32_16x16x32_bf16 v[48:51], v[136:139], v[184:187], v[48:51]
	v_mfma_f32_16x16x32_bf16 v[44:47], v[144:147], v[184:187], v[44:47]
	v_mfma_f32_16x16x32_bf16 v[40:43], v[136:139], v[192:195], v[40:43]
	v_mfma_f32_16x16x32_bf16 v[36:39], v[144:147], v[192:195], v[36:39]
	s_setprio 0
	s_setprio 1
	v_mfma_f32_16x16x32_bf16 v[32:35], v[148:151], v[164:167], v[32:35]
	v_mfma_f32_16x16x32_bf16 v[28:31], v[156:159], v[164:167], v[28:31]
	v_mfma_f32_16x16x32_bf16 v[24:27], v[148:151], v[172:175], v[24:27]
	v_mfma_f32_16x16x32_bf16 v[20:23], v[156:159], v[172:175], v[20:23]
	v_mfma_f32_16x16x32_bf16 v[16:19], v[148:151], v[180:183], v[16:19]
	v_mfma_f32_16x16x32_bf16 v[12:15], v[156:159], v[180:183], v[12:15]
	v_mfma_f32_16x16x32_bf16 v[6:9], v[148:151], v[188:191], v[8:11]
	v_mfma_f32_16x16x32_bf16 v[2:5], v[156:159], v[188:191], v[2:5]
	v_mfma_f32_16x16x32_bf16 v[32:35], v[152:155], v[168:171], v[32:35]
	v_mfma_f32_16x16x32_bf16 v[28:31], v[160:163], v[168:171], v[28:31]
	v_mfma_f32_16x16x32_bf16 v[24:27], v[152:155], v[176:179], v[24:27]
	v_mfma_f32_16x16x32_bf16 v[20:23], v[160:163], v[176:179], v[20:23]
	v_mfma_f32_16x16x32_bf16 v[16:19], v[152:155], v[184:187], v[16:19]
	v_mfma_f32_16x16x32_bf16 v[12:15], v[160:163], v[184:187], v[12:15]
	v_mfma_f32_16x16x32_bf16 v[8:11], v[152:155], v[192:195], v[6:9]
	v_mfma_f32_16x16x32_bf16 v[4:7], v[160:163], v[192:195], v[2:5]
	s_setprio 0
	s_barrier
	s_add_u32 s70, s70, 0x100
	s_addc_u32 s71, s71, 0
	s_add_u32 s50, s50, 0x100
	s_addc_u32 s51, s51, 0
	s_cmp_ge_i32 s72, s62
	s_mov_b32 s52, s72
	s_cbranch_scc0 .LBB0_889

; __device__ __forceinline__ u32x4 pack8(f32x4 a, f32x4 b) { u32x4 w; w.x = cvt_pk_bf16(a[0], a[1]); w.y = cvt_pk_bf16(a[2], a[3]); w.z = cvt_pk_bf16(b[0], b[1]); w.w = cvt_pk_bf16(b[2], b[3]); return w; }
; __device__ __forceinline__ void unpack8(u32x4 w, f32x4& a, f32x4& b) { a = (f32x4){bf_lo(w.x), bf_hi(w.x), bf_lo(w.y), bf_hi(w.y)}; b = (f32x4){bf_lo(w.z), bf_hi(w.z), bf_lo(w.w), bf_hi(w.w)}; }
; #define ST16(BASE, OFF, VAL) __builtin_amdgcn_raw_buffer_store_b128((VAL), __builtin_amdgcn_make_buffer_rsrc((void*)(BASE), (short)0, 0x7ffffff0, 0x00020000), (int)((unsigned)(OFF) * (unsigned)sizeof(*(BASE))), 0, ST_AUX)
;     __device__ __forceinline__ void operator()(Acc& acc, const Unit& u, int wr, int wc, int fr, int fq) const {
;     ...
;         for (int ai = 0; ai < 2; ++ai) {
;             u32x4 gw_[4][2], hw_[4][2];
; #pragma unroll
;             for (int m = 0; m < 4; ++m)
; #pragma unroll
;                 for (int bj = 0; bj < 2; ++bj) { const unsigned o = (unsigned)((rowt + ai * 128 + m * 16) * 2048 + c0 + bj * 128);
;                     gw_[m][bj] = *(const u32x4*)(GATES + (o + 1024)); if (u.sel == 0) hw_[m][bj] = *(const u32x4*)(GATES + o); else hw_[m][bj] = gw_[m][bj]; }
; #pragma unroll
;             for (int m = 0; m < 4; ++m) { const unsigned row = rowt + ai * 128 + m * 16;
; #pragma unroll
;                 for (int bj = 0; bj < 2; ++bj) { f32x4 r0, r1, a0, a1; unpack8(gw_[m][bj], r0, r1); unpack8(hw_[m][bj], a0, a1);
;                     if (u.sel == 0) {
; #pragma unroll
;                         for (int e = 0; e < 4; ++e) { acc[ai][bj][m][0][e] *= a0[e] * __builtin_amdgcn_rcpf(r0[e]); acc[ai][bj][m][1][e] *= a1[e] * __builtin_amdgcn_rcpf(r1[e]); } }
;                     else { ST16(MERGED, (row * 1024 + c0 + bj * 128), pack8(acc[ai][bj][m][0] * r0, acc[ai][bj][m][1] * r1)); } } }
.LBB0_892:
	v_lshl_or_b32 v212, s6, 8, v221
	s_lshl_b32 s4, s4, 19
	v_add3_u32 v2, s4, v220, v212
	s_waitcnt vmcnt(0)
	s_cmp_eq_u32 s5, 0
	s_cselect_b64 s[6:7], -1, 0
	s_cmp_lg_u32 s5, 0
	s_cselect_b64 s[50:51], -1, 0
	v_cndmask_b32_e64 v0, 0, 1, s[6:7]
	v_cmp_ne_u32_e64 s[4:5], 1, v0
	v_add_u32_e32 v0, 0x400, v2
	v_lshl_add_u64 v[132:133], v[0:1], 1, s[16:17]
	global_load_dwordx4 v[192:195], v[132:133], off
	v_add_u32_e32 v0, 0x480, v2
	v_lshl_add_u64 v[132:133], v[0:1], 1, s[16:17]
	global_load_dwordx4 v[184:187], v[132:133], off
	v_add_u32_e32 v0, 0x8400, v2
	v_lshl_add_u64 v[132:133], v[0:1], 1, s[16:17]
	global_load_dwordx4 v[176:179], v[132:133], off
	v_add_u32_e32 v0, 0x8480, v2
	v_lshl_add_u64 v[132:133], v[0:1], 1, s[16:17]
	global_load_dwordx4 v[168:171], v[132:133], off
	v_add_u32_e32 v0, 0x10400, v2
	v_lshl_add_u64 v[132:133], v[0:1], 1, s[16:17]
	global_load_dwordx4 v[160:163], v[132:133], off
	v_add_u32_e32 v0, 0x10480, v2
	v_lshl_add_u64 v[132:133], v[0:1], 1, s[16:17]
	global_load_dwordx4 v[152:155], v[132:133], off
	v_add_u32_e32 v0, 0x18400, v2
	v_lshl_add_u64 v[132:133], v[0:1], 1, s[16:17]
	global_load_dwordx4 v[144:147], v[132:133], off
	v_add_u32_e32 v0, 0x18480, v2
	v_lshl_add_u64 v[132:133], v[0:1], 1, s[16:17]
	global_load_dwordx4 v[136:139], v[132:133], off
	s_and_b64 vcc, exec, s[4:5]
	s_cbranch_vccnz .Lp5_cp_A
	v_mov_b32_e32 v3, v1
	v_lshl_add_u64 v[132:133], v[2:3], 1, s[16:17]
	global_load_dwordx4 v[188:191], v[132:133], off
	v_or_b32_e32 v0, 0x80, v2
	v_lshl_add_u64 v[132:133], v[0:1], 1, s[16:17]
	global_load_dwordx4 v[180:183], v[132:133], off
	v_add_u32_e32 v0, 0x8000, v2
	v_lshl_add_u64 v[132:133], v[0:1], 1, s[16:17]
	global_load_dwordx4 v[172:175], v[132:133], off
	v_add_u32_e32 v0, 0x8080, v2
	v_lshl_add_u64 v[132:133], v[0:1], 1, s[16:17]
	global_load_dwordx4 v[164:167], v[132:133], off
	v_add_u32_e32 v0, 0x10000, v2
	v_lshl_add_u64 v[132:133], v[0:1], 1, s[16:17]
	global_load_dwordx4 v[156:159], v[132:133], off
	v_add_u32_e32 v0, 0x10080, v2
	v_lshl_add_u64 v[132:133], v[0:1], 1, s[16:17]
	global_load_dwordx4 v[148:151], v[132:133], off
	v_add_u32_e32 v0, 0x18000, v2
	v_lshl_add_u64 v[132:133], v[0:1], 1, s[16:17]
	global_load_dwordx4 v[140:143], v[132:133], off
	v_add_u32_e32 v0, 0x18080, v2
	v_lshl_add_u64 v[132:133], v[0:1], 1, s[16:17]
	global_load_dwordx4 v[132:135], v[132:133], off
	s_waitcnt vmcnt(0)
	s_branch .Lp5_end_A
.Lp5_cp_A:
	s_waitcnt vmcnt(0)
	v_mov_b64_e32 v[188:189], v[192:193]
	v_mov_b64_e32 v[190:191], v[194:195]
	v_mov_b64_e32 v[180:181], v[184:185]
	v_mov_b64_e32 v[182:183], v[186:187]
	v_mov_b64_e32 v[172:173], v[176:177]
	v_mov_b64_e32 v[174:175], v[178:179]
	v_mov_b64_e32 v[164:165], v[168:169]
	v_mov_b64_e32 v[166:167], v[170:171]
	v_mov_b64_e32 v[156:157], v[160:161]
	v_mov_b64_e32 v[158:159], v[162:163]
	v_mov_b64_e32 v[148:149], v[152:153]
	v_mov_b64_e32 v[150:151], v[154:155]
	v_mov_b64_e32 v[140:141], v[144:145]
	v_mov_b64_e32 v[142:143], v[146:147]
	v_mov_b64_e32 v[132:133], v[136:137]
	v_mov_b64_e32 v[134:135], v[138:139]
.Lp5_end_A:
.LBB0_908:
	v_add_u32_e32 v223, v2, v212
	v_lshlrev_b32_e32 v216, 16, v192
	v_and_b32_e32 v217, 0xffff0000, v192
	v_lshlrev_b32_e32 v212, 16, v193
	v_and_b32_e32 v213, 0xffff0000, v193
	v_lshlrev_b32_e32 v214, 16, v194
	v_and_b32_e32 v215, 0xffff0000, v194
	v_lshlrev_b32_e32 v192, 16, v195
	v_and_b32_e32 v193, 0xffff0000, v195
	s_mov_b64 s[6:7], -1
	s_and_b64 vcc, exec, s[50:51]
	s_cbranch_vccz .LBB0_910
	v_pk_mul_f32 v[224:225], v[128:129], v[216:217]
	v_pk_mul_f32 v[226:227], v[124:125], v[214:215]
	v_pk_mul_f32 v[194:195], v[130:131], v[212:213]
	v_pk_mul_f32 v[228:229], v[126:127], v[192:193]
	v_cvt_pk_bf16_f32 v224, v224, v225
	v_cvt_pk_bf16_f32 v225, v194, v195
	v_cvt_pk_bf16_f32 v226, v226, v227
	s_mov_b64 s[6:7], 0
	v_cvt_pk_bf16_f32 v227, v228, v229
	buffer_store_dwordx4 v[224:227], v223, s[8:11], 0 offen nt

; __device__ __forceinline__ void unpack8(u32x4 w, f32x4& a, f32x4& b) { a = (f32x4){bf_lo(w.x), bf_hi(w.x), bf_lo(w.y), bf_hi(w.y)}; b = (f32x4){bf_lo(w.z), bf_hi(w.z), bf_lo(w.w), bf_hi(w.w)}; }
;     __device__ __forceinline__ void operator()(Acc& acc, const Unit& u, int wr, int wc, int fr, int fq) const {
;     ...
;         for (int ai = 0; ai < 2; ++ai) {
;             u32x4 gw_[4][2], hw_[4][2];
; #pragma unroll
;             for (int m = 0; m < 4; ++m)
; #pragma unroll
;                 for (int bj = 0; bj < 2; ++bj) { const unsigned o = (unsigned)((rowt + ai * 128 + m * 16) * 2048 + c0 + bj * 128);
;                     gw_[m][bj] = *(const u32x4*)(GATES + (o + 1024)); if (u.sel == 0) hw_[m][bj] = *(const u32x4*)(GATES + o); else hw_[m][bj] = gw_[m][bj]; }
; #pragma unroll
;             for (int m = 0; m < 4; ++m) { const unsigned row = rowt + ai * 128 + m * 16;
; #pragma unroll
;                 for (int bj = 0; bj < 2; ++bj) { f32x4 r0, r1, a0, a1; unpack8(gw_[m][bj], r0, r1); unpack8(hw_[m][bj], a0, a1);
.LBB0_940:
	s_waitcnt vmcnt(0)
	v_add_u32_e32 v0, 0x40400, v2
	v_lshl_add_u64 v[132:133], v[0:1], 1, s[16:17]
	global_load_dwordx4 v[192:195], v[132:133], off
	v_add_u32_e32 v0, 0x40480, v2
	v_lshl_add_u64 v[132:133], v[0:1], 1, s[16:17]
	global_load_dwordx4 v[184:187], v[132:133], off
	v_add_u32_e32 v0, 0x48400, v2
	v_lshl_add_u64 v[132:133], v[0:1], 1, s[16:17]
	global_load_dwordx4 v[176:179], v[132:133], off
	v_add_u32_e32 v0, 0x48480, v2
	v_lshl_add_u64 v[132:133], v[0:1], 1, s[16:17]
	global_load_dwordx4 v[168:171], v[132:133], off
	v_add_u32_e32 v0, 0x50400, v2
	v_lshl_add_u64 v[132:133], v[0:1], 1, s[16:17]
	global_load_dwordx4 v[160:163], v[132:133], off
	v_add_u32_e32 v0, 0x50480, v2
	v_lshl_add_u64 v[132:133], v[0:1], 1, s[16:17]
	global_load_dwordx4 v[152:155], v[132:133], off
	v_add_u32_e32 v0, 0x58400, v2
	v_lshl_add_u64 v[132:133], v[0:1], 1, s[16:17]
	global_load_dwordx4 v[144:147], v[132:133], off
	v_add_u32_e32 v0, 0x58480, v2
	v_lshl_add_u64 v[132:133], v[0:1], 1, s[16:17]
	global_load_dwordx4 v[136:139], v[132:133], off
	s_and_b64 vcc, exec, s[4:5]
	s_cbranch_vccnz .Lp5_cp_B
	v_add_u32_e32 v0, 0x40000, v2
	v_lshl_add_u64 v[132:133], v[0:1], 1, s[16:17]
	global_load_dwordx4 v[188:191], v[132:133], off
	v_add_u32_e32 v0, 0x40080, v2
	v_lshl_add_u64 v[132:133], v[0:1], 1, s[16:17]
	global_load_dwordx4 v[180:183], v[132:133], off
	v_add_u32_e32 v0, 0x48000, v2
	v_lshl_add_u64 v[132:133], v[0:1], 1, s[16:17]
	global_load_dwordx4 v[172:175], v[132:133], off
	v_add_u32_e32 v0, 0x48080, v2
	v_lshl_add_u64 v[132:133], v[0:1], 1, s[16:17]
	global_load_dwordx4 v[164:167], v[132:133], off
	v_add_u32_e32 v0, 0x50000, v2
	v_lshl_add_u64 v[132:133], v[0:1], 1, s[16:17]
	global_load_dwordx4 v[156:159], v[132:133], off
	v_add_u32_e32 v0, 0x50080, v2
	v_lshl_add_u64 v[132:133], v[0:1], 1, s[16:17]
	global_load_dwordx4 v[148:151], v[132:133], off
	v_add_u32_e32 v0, 0x58000, v2
	v_lshl_add_u64 v[132:133], v[0:1], 1, s[16:17]
	global_load_dwordx4 v[140:143], v[132:133], off
	v_add_u32_e32 v0, 0x58080, v2
	v_lshl_add_u64 v[2:3], v[0:1], 1, s[16:17]
	global_load_dwordx4 v[132:135], v[2:3], off
	s_waitcnt vmcnt(0)
	s_branch .Lp5_end_B

; __device__ __forceinline__ u32x4 pack8(f32x4 a, f32x4 b) { u32x4 w; w.x = cvt_pk_bf16(a[0], a[1]); w.y = cvt_pk_bf16(a[2], a[3]); w.z = cvt_pk_bf16(b[0], b[1]); w.w = cvt_pk_bf16(b[2], b[3]); return w; }
; __device__ __forceinline__ void unpack8(u32x4 w, f32x4& a, f32x4& b) { a = (f32x4){bf_lo(w.x), bf_hi(w.x), bf_lo(w.y), bf_hi(w.y)}; b = (f32x4){bf_lo(w.z), bf_hi(w.z), bf_lo(w.w), bf_hi(w.w)}; }
; #define ST16(BASE, OFF, VAL) __builtin_amdgcn_raw_buffer_store_b128((VAL), __builtin_amdgcn_make_buffer_rsrc((void*)(BASE), (short)0, 0x7ffffff0, 0x00020000), (int)((unsigned)(OFF) * (unsigned)sizeof(*(BASE))), 0, ST_AUX)
;     __device__ __forceinline__ void operator()(Acc& acc, const Unit& u, int wr, int wc, int fr, int fq) const {
;     ...
;             for (int m = 0; m < 4; ++m) { const unsigned row = rowt + ai * 128 + m * 16;
; #pragma unroll
;                 for (int bj = 0; bj < 2; ++bj) { f32x4 r0, r1, a0, a1; unpack8(gw_[m][bj], r0, r1); unpack8(hw_[m][bj], a0, a1);
;                     if (u.sel == 0) {
; #pragma unroll
;                         for (int e = 0; e < 4; ++e) { acc[ai][bj][m][0][e] *= a0[e] * __builtin_amdgcn_rcpf(r0[e]); acc[ai][bj][m][1][e] *= a1[e] * __builtin_amdgcn_rcpf(r1[e]); } }
;                     else { ST16(MERGED, (row * 1024 + c0 + bj * 128), pack8(acc[ai][bj][m][0] * r0, acc[ai][bj][m][1] * r1)); } } }
.Lp5_end_B:
.LBB0_956:
	v_lshlrev_b32_e32 v214, 16, v192
	v_and_b32_e32 v215, 0xffff0000, v192
	v_lshlrev_b32_e32 v192, 16, v193
	v_and_b32_e32 v193, 0xffff0000, v193
	v_lshlrev_b32_e32 v212, 16, v194
	v_and_b32_e32 v213, 0xffff0000, v194
	v_lshlrev_b32_e32 v2, 16, v195
	v_and_b32_e32 v3, 0xffff0000, v195
	s_mov_b64 s[4:5], -1
	s_and_b64 vcc, exec, s[6:7]
	v_add_u32_e32 v0, 0x40000, v223
	s_cbranch_vccnz .LBB0_958
	v_pk_mul_f32 v[226:227], v[60:61], v[212:213]
	s_mov_b64 s[4:5], 0
	v_pk_mul_f32 v[194:195], v[66:67], v[192:193]
	v_pk_mul_f32 v[216:217], v[64:65], v[214:215]
	v_pk_mul_f32 v[228:229], v[62:63], v[2:3]
	v_cvt_pk_bf16_f32 v224, v216, v217
	v_cvt_pk_bf16_f32 v225, v194, v195
	v_cvt_pk_bf16_f32 v226, v226, v227
	s_nop 0
	v_cvt_pk_bf16_f32 v227, v228, v229
	buffer_store_dwordx4 v[224:227], v0, s[8:11], 0 offen nt

;     __device__ __forceinline__ const char* a_ptr(const Unit& u) const { return (const char*)(u.sel ? A1 : A0) + ((size_t)u.pm * BM * lda + (size_t)(u.pn >> a_grp_shift) * a_grp_cols) * 2; }
;     __device__ __forceinline__ const char* b_ptr(const Unit& u) const { return (const char*)(u.sel ? B1 : B0) + (size_t)u.pn * BM * ldb * 2; }
;     __device__ bool next(int i, Unit& u) const { if (!S.next(i >> 1, u)) return false; u.sel = i & 1; return true; }
; template <class Epi, class Sched, bool ALIGN_EPI>
; __device__ __forceinline__ void gemm_phase(LAS unsigned char* lds, const Gemm g, const Sched& S, const Epi& E) {
;     ...
;         const bool has_next = S.next(ui + 1, nxt);
;         const char* nA = has_next ? g.a_ptr(nxt) : cA; const char* nB = has_next ? g.b_ptr(nxt) : cB;
;     __device__ __forceinline__ void operator()(const Acc& acc, const Unit& u, int wr, int wc, int fr, int fq) const {
;         const int rowt = u.pm * 256 + wr * 64 + fr, c0 = u.pn * 128 + wc * 32 + 8 * fq;
;         float ss[8];
; #pragma unroll
;         for (int i = 0; i < 8; ++i) ss[i] = SS2[(unsigned)(rowt + (i >> 2) * 128 + (i & 3) * 16)];
.LBB0_1147:
	s_ashr_i32 s39, s38, 31
	s_lshl_b64 s[40:41], s[38:39], 19
	s_add_u32 s40, s14, s40
	s_addc_u32 s41, s15, s41
	s_ashr_i32 s37, s36, 31
	s_lshl_b64 s[42:43], s[36:37], 19
	s_add_u32 s42, s76, s42
	s_addc_u32 s43, s77, s43
	s_and_b64 vcc, exec, s[0:1]
	s_cbranch_vccnz .Lzstub_5
	v_lshl_add_u32 v254, s44, 8, v146
	v_mov_b32_e32 v255, 0
	s_nop 0
	v_lshl_add_u64 v[254:255], v[254:255], 2, s[6:7]
	global_load_dword v240, v[254:255], off
	global_load_dword v241, v[254:255], off offset:64
	global_load_dword v242, v[254:255], off offset:128
	global_load_dword v243, v[254:255], off offset:192
	global_load_dword v244, v[254:255], off offset:512
	global_load_dword v245, v[254:255], off offset:576
	global_load_dword v246, v[254:255], off offset:640
	global_load_dword v247, v[254:255], off offset:704
	s_and_b64 s[66:67], s[4:5], exec
	s_cselect_b32 s37, s41, s49
	s_cselect_b32 s39, s40, s48
	s_cselect_b32 s66, s43, s47
	s_cselect_b32 s67, s42, s46
	s_add_u32 s68, s46, 0x100
	s_addc_u32 s69, s47, 0
	s_add_u32 s46, s48, 0x80
	v_mov_b32_e32 v0, 0
	s_addc_u32 s47, s49, 0
	s_mov_b32 s48, 0
	v_mov_b32_e32 v1, v0
	v_mov_b32_e32 v2, v0
	v_mov_b32_e32 v3, v0
	v_mov_b32_e32 v12, v0
	v_mov_b32_e32 v13, v0
	v_mov_b32_e32 v14, v0
	v_mov_b32_e32 v15, v0
	v_mov_b32_e32 v20, v0
	v_mov_b32_e32 v21, v0
	v_mov_b32_e32 v22, v0
	v_mov_b32_e32 v23, v0
	v_mov_b32_e32 v28, v0
	v_mov_b32_e32 v29, v0
	v_mov_b32_e32 v30, v0
	v_mov_b32_e32 v31, v0
	v_mov_b32_e32 v36, v0
	v_mov_b32_e32 v37, v0
	v_mov_b32_e32 v38, v0
	v_mov_b32_e32 v39, v0
	v_mov_b32_e32 v44, v0
	v_mov_b32_e32 v45, v0
	v_mov_b32_e32 v46, v0
	v_mov_b32_e32 v47, v0
	v_mov_b32_e32 v52, v0
	v_mov_b32_e32 v53, v0
	v_mov_b32_e32 v54, v0
	v_mov_b32_e32 v55, v0
	v_mov_b32_e32 v60, v0
	v_mov_b32_e32 v61, v0
	v_mov_b32_e32 v62, v0
	v_mov_b32_e32 v63, v0
	v_mov_b32_e32 v4, v0
	v_mov_b32_e32 v5, v0
	v_mov_b32_e32 v6, v0
	v_mov_b32_e32 v7, v0
	v_mov_b32_e32 v8, v0
	v_mov_b32_e32 v9, v0
	v_mov_b32_e32 v10, v0
	v_mov_b32_e32 v11, v0
	v_mov_b32_e32 v16, v0
	v_mov_b32_e32 v17, v0
	v_mov_b32_e32 v18, v0
	v_mov_b32_e32 v19, v0
	v_mov_b32_e32 v24, v0
	v_mov_b32_e32 v25, v0
	v_mov_b32_e32 v26, v0
	v_mov_b32_e32 v27, v0
	v_mov_b32_e32 v32, v0
	v_mov_b32_e32 v33, v0
	v_mov_b32_e32 v34, v0
	v_mov_b32_e32 v35, v0
	v_mov_b32_e32 v40, v0
	v_mov_b32_e32 v41, v0
	v_mov_b32_e32 v42, v0
	v_mov_b32_e32 v43, v0
	v_mov_b32_e32 v48, v0
	v_mov_b32_e32 v49, v0
	v_mov_b32_e32 v50, v0
	v_mov_b32_e32 v51, v0
	v_mov_b32_e32 v56, v0
	v_mov_b32_e32 v57, v0
	v_mov_b32_e32 v58, v0
	v_mov_b32_e32 v59, v0
	v_mov_b32_e32 v68, v0
	v_mov_b32_e32 v69, v0
	v_mov_b32_e32 v70, v0
	v_mov_b32_e32 v71, v0
	v_mov_b32_e32 v76, v0
	v_mov_b32_e32 v77, v0
	v_mov_b32_e32 v78, v0
	v_mov_b32_e32 v79, v0
	v_mov_b32_e32 v84, v0
	v_mov_b32_e32 v85, v0
	v_mov_b32_e32 v86, v0
	v_mov_b32_e32 v87, v0
	v_mov_b32_e32 v92, v0
	v_mov_b32_e32 v93, v0
	v_mov_b32_e32 v94, v0
	v_mov_b32_e32 v95, v0
	v_mov_b32_e32 v100, v0
	v_mov_b32_e32 v101, v0
	v_mov_b32_e32 v102, v0
	v_mov_b32_e32 v103, v0
	v_mov_b32_e32 v108, v0
	v_mov_b32_e32 v109, v0
	v_mov_b32_e32 v110, v0
	v_mov_b32_e32 v111, v0
	v_mov_b32_e32 v120, v0
	v_mov_b32_e32 v121, v0
	v_mov_b32_e32 v122, v0
	v_mov_b32_e32 v123, v0
	v_mov_b32_e32 v124, v0
	v_mov_b32_e32 v125, v0
	v_mov_b32_e32 v126, v0
	v_mov_b32_e32 v127, v0
	v_mov_b32_e32 v64, v0
	v_mov_b32_e32 v65, v0
	v_mov_b32_e32 v66, v0
	v_mov_b32_e32 v67, v0
	v_mov_b32_e32 v72, v0
	v_mov_b32_e32 v73, v0
	v_mov_b32_e32 v74, v0
	v_mov_b32_e32 v75, v0
	v_mov_b32_e32 v80, v0
	v_mov_b32_e32 v81, v0
	v_mov_b32_e32 v82, v0
	v_mov_b32_e32 v83, v0
	v_mov_b32_e32 v88, v0
	v_mov_b32_e32 v89, v0
	v_mov_b32_e32 v90, v0
	v_mov_b32_e32 v91, v0
	v_mov_b32_e32 v96, v0
	v_mov_b32_e32 v97, v0
	v_mov_b32_e32 v98, v0
	v_mov_b32_e32 v99, v0
	v_mov_b32_e32 v104, v0
	v_mov_b32_e32 v105, v0
	v_mov_b32_e32 v106, v0
	v_mov_b32_e32 v107, v0
	v_mov_b32_e32 v112, v0
	v_mov_b32_e32 v113, v0
	v_mov_b32_e32 v114, v0
	v_mov_b32_e32 v115, v0
	v_mov_b32_e32 v116, v0
	v_mov_b32_e32 v117, v0
	v_mov_b32_e32 v118, v0
	v_mov_b32_e32 v119, v0

; __device__ __forceinline__ float fsigmoid(float x) { return __builtin_amdgcn_rcpf(1.0f + __builtin_amdgcn_exp2f(-x * LOG2E)); }
; __device__ __forceinline__ u32x4 pack8(f32x4 a, f32x4 b) { u32x4 w; w.x = cvt_pk_bf16(a[0], a[1]); w.y = cvt_pk_bf16(a[2], a[3]); w.z = cvt_pk_bf16(b[0], b[1]); w.w = cvt_pk_bf16(b[2], b[3]); return w; }
; #define ST16(BASE, OFF, VAL) __builtin_amdgcn_raw_buffer_store_b128((VAL), __builtin_amdgcn_make_buffer_rsrc((void*)(BASE), (short)0, 0x7ffffff0, 0x00020000), (int)((unsigned)(OFF) * (unsigned)sizeof(*(BASE))), 0, ST_AUX)
;     __device__ __forceinline__ void operator()(const Acc& acc, const Unit& u, int wr, int wc, int fr, int fq) const {
;         const int rowt = u.pm * 256 + wr * 64 + fr, c0 = u.pn * 128 + wc * 32 + 8 * fq;
;         float ss[8];
; #pragma unroll
;         for (int i = 0; i < 8; ++i) ss[i] = SS2[(unsigned)(rowt + (i >> 2) * 128 + (i & 3) * 16)];
; #pragma unroll
;         for (int ai = 0; ai < 2; ++ai)
; #pragma unroll
;             for (int m = 0; m < 4; ++m) { const unsigned row = rowt + ai * 128 + m * 16; const float rstd = rsqrtf(ss[ai * 4 + m] * (1.0f / 1024.0f) + EPS);
;                 f32x4 h0, h1;
; #pragma unroll
;                 for (int e = 0; e < 4; ++e) { const float g0 = acc[ai][0][m][0][e] * rstd, g1 = acc[ai][0][m][1][e] * rstd;
;                     h0[e] = g0 * fsigmoid(g0) * (acc[ai][1][m][0][e] * rstd); h1[e] = g1 * fsigmoid(g1) * (acc[ai][1][m][1][e] * rstd); }
;                 ST16(HID, (row * DFF + c0), pack8(h0, h1)); }
.LBB0_1152:
	s_waitcnt vmcnt(8)
	v_lshl_add_u32 v136, s44, 8, v146
	v_lshl_or_b32 v174, s65, 7, v148
	v_mul_lo_u32 v175, v136, s64
	v_fmamk_f32 v153, v240, 0x3a800000, v152
	v_fmamk_f32 v154, v241, 0x3a800000, v152
	v_fmamk_f32 v155, v242, 0x3a800000, v152
	v_fmamk_f32 v156, v243, 0x3a800000, v152
	v_fmamk_f32 v157, v244, 0x3a800000, v152
	v_fmamk_f32 v158, v245, 0x3a800000, v152
	v_fmamk_f32 v159, v246, 0x3a800000, v152
	v_fmamk_f32 v160, v247, 0x3a800000, v152
	v_mul_f32_e32 v161, 0x4b800000, v153
	v_mul_f32_e32 v162, 0x4b800000, v154
	v_mul_f32_e32 v163, 0x4b800000, v155
	v_mul_f32_e32 v164, 0x4b800000, v156
	v_mul_f32_e32 v165, 0x4b800000, v157
	v_mul_f32_e32 v166, 0x4b800000, v158
	v_mul_f32_e32 v167, 0x4b800000, v159
	v_mul_f32_e32 v168, 0x4b800000, v160
	v_cmp_gt_f32_e32 vcc, s63, v153
	s_nop 1
	v_cndmask_b32_e32 v153, v153, v161, vcc
	v_rsq_f32_e32 v240, v153
	s_nop 0
	v_mul_f32_e32 v161, 0x45800000, v240
	v_cndmask_b32_e32 v240, v240, v161, vcc
	v_cmp_gt_f32_e32 vcc, s63, v154
	s_nop 1
	v_cndmask_b32_e32 v154, v154, v162, vcc
	v_rsq_f32_e32 v241, v154
	s_nop 0
	v_mul_f32_e32 v162, 0x45800000, v241
	v_cndmask_b32_e32 v241, v241, v162, vcc
	v_cmp_gt_f32_e32 vcc, s63, v155
	s_nop 1
	v_cndmask_b32_e32 v155, v155, v163, vcc
	v_rsq_f32_e32 v242, v155
	s_nop 0
	v_mul_f32_e32 v163, 0x45800000, v242
	v_cndmask_b32_e32 v242, v242, v163, vcc
	v_cmp_gt_f32_e32 vcc, s63, v156
	s_nop 1
	v_cndmask_b32_e32 v156, v156, v164, vcc
	v_rsq_f32_e32 v243, v156
	s_nop 0
	v_mul_f32_e32 v164, 0x45800000, v243
	v_cndmask_b32_e32 v243, v243, v164, vcc
	v_cmp_gt_f32_e32 vcc, s63, v157
	s_nop 1
	v_cndmask_b32_e32 v157, v157, v165, vcc
	v_rsq_f32_e32 v244, v157
	s_nop 0
	v_mul_f32_e32 v165, 0x45800000, v244
	v_cndmask_b32_e32 v244, v244, v165, vcc
	v_cmp_gt_f32_e32 vcc, s63, v158
	s_nop 1
	v_cndmask_b32_e32 v158, v158, v166, vcc
	v_rsq_f32_e32 v245, v158
	s_nop 0
	v_mul_f32_e32 v166, 0x45800000, v245
	v_cndmask_b32_e32 v245, v245, v166, vcc
	v_cmp_gt_f32_e32 vcc, s63, v159
	s_nop 1
	v_cndmask_b32_e32 v159, v159, v167, vcc
	v_rsq_f32_e32 v246, v159
	s_nop 0
	v_mul_f32_e32 v167, 0x45800000, v246
	v_cndmask_b32_e32 v246, v246, v167, vcc
	v_cmp_gt_f32_e32 vcc, s63, v160
	s_nop 1
	v_cndmask_b32_e32 v160, v160, v168, vcc
	v_rsq_f32_e32 v247, v160
	s_nop 0
	v_mul_f32_e32 v168, 0x45800000, v247
	v_cndmask_b32_e32 v247, v247, v168, vcc
	v_add_lshl_u32 v136, v175, v174, 1
	v_mul_f32_e32 v116, v116, v240
	v_mul_f32_e32 v117, v117, v240
	v_mul_f32_e32 v118, v118, v240
	v_mul_f32_e32 v119, v119, v240
	v_mul_f32_e32 v124, v124, v240
	v_mul_f32_e32 v125, v125, v240
	v_mul_f32_e32 v126, v126, v240
	v_mul_f32_e32 v127, v127, v240
	v_mul_f32_e32 v248, 0xbfb8aa3b, v116
	v_mul_f32_e32 v249, 0xbfb8aa3b, v117
	v_mul_f32_e32 v250, 0xbfb8aa3b, v118
	v_mul_f32_e32 v251, 0xbfb8aa3b, v119
	v_exp_f32_e32 v248, v248
	v_exp_f32_e32 v249, v249
	v_exp_f32_e32 v250, v250
	v_exp_f32_e32 v251, v251
	v_add_f32_e32 v248, 1.0, v248
	v_add_f32_e32 v249, 1.0, v249
	v_add_f32_e32 v250, 1.0, v250
	v_add_f32_e32 v251, 1.0, v251
	v_rcp_f32_e32 v248, v248
	v_rcp_f32_e32 v249, v249
	v_rcp_f32_e32 v250, v250
	v_rcp_f32_e32 v251, v251
	v_mul_f32_e32 v116, v116, v248
	v_mul_f32_e32 v117, v117, v249
	v_mul_f32_e32 v118, v118, v250
	v_mul_f32_e32 v119, v119, v251
	v_mul_f32_e32 v116, v124, v116
	v_mul_f32_e32 v117, v125, v117
	v_mul_f32_e32 v118, v126, v118
	v_mul_f32_e32 v119, v127, v119
	v_mul_f32_e32 v112, v112, v240
	v_mul_f32_e32 v113, v113, v240
	v_mul_f32_e32 v114, v114, v240
	v_mul_f32_e32 v115, v115, v240
	v_mul_f32_e32 v120, v120, v240
	v_mul_f32_e32 v121, v121, v240
	v_mul_f32_e32 v122, v122, v240
	v_mul_f32_e32 v123, v123, v240
	v_mul_f32_e32 v248, 0xbfb8aa3b, v112
	v_mul_f32_e32 v249, 0xbfb8aa3b, v113
	v_mul_f32_e32 v250, 0xbfb8aa3b, v114
	v_mul_f32_e32 v251, 0xbfb8aa3b, v115
	v_exp_f32_e32 v248, v248
	v_exp_f32_e32 v249, v249
	v_exp_f32_e32 v250, v250
	v_exp_f32_e32 v251, v251
	v_add_f32_e32 v248, 1.0, v248
	v_add_f32_e32 v249, 1.0, v249
	v_add_f32_e32 v250, 1.0, v250
	v_add_f32_e32 v251, 1.0, v251
	v_rcp_f32_e32 v248, v248
	v_rcp_f32_e32 v249, v249
	v_rcp_f32_e32 v250, v250
	v_rcp_f32_e32 v251, v251
	v_mul_f32_e32 v112, v112, v248
	v_mul_f32_e32 v113, v113, v249
	v_mul_f32_e32 v114, v114, v250
	v_mul_f32_e32 v115, v115, v251
	v_mul_f32_e32 v112, v120, v112
	v_mul_f32_e32 v113, v121, v113
	v_mul_f32_e32 v114, v122, v114
	v_mul_f32_e32 v115, v123, v115
	v_cvt_pk_bf16_f32 v116, v116, v117
	v_cvt_pk_bf16_f32 v117, v118, v119
	v_cvt_pk_bf16_f32 v118, v112, v113
	v_cvt_pk_bf16_f32 v119, v114, v115
	buffer_store_dwordx4 v[116:119], v136, s[8:11], 0 offen nt
	v_mul_f32_e32 v104, v104, v241
	v_mul_f32_e32 v105, v105, v241
	v_mul_f32_e32 v106, v106, v241
	v_mul_f32_e32 v107, v107, v241
	v_mul_f32_e32 v108, v108, v241
	v_mul_f32_e32 v109, v109, v241
	v_mul_f32_e32 v110, v110, v241
	v_mul_f32_e32 v111, v111, v241
	v_mul_f32_e32 v248, 0xbfb8aa3b, v104
	v_mul_f32_e32 v249, 0xbfb8aa3b, v105
	v_mul_f32_e32 v250, 0xbfb8aa3b, v106
	v_mul_f32_e32 v251, 0xbfb8aa3b, v107
	v_exp_f32_e32 v248, v248
	v_exp_f32_e32 v249, v249
	v_exp_f32_e32 v250, v250
	v_exp_f32_e32 v251, v251
	v_add_f32_e32 v248, 1.0, v248
	v_add_f32_e32 v249, 1.0, v249
	v_add_f32_e32 v250, 1.0, v250
	v_add_f32_e32 v251, 1.0, v251
	v_rcp_f32_e32 v248, v248
	v_rcp_f32_e32 v249, v249
	v_rcp_f32_e32 v250, v250
	v_rcp_f32_e32 v251, v251
	v_mul_f32_e32 v104, v104, v248
	v_mul_f32_e32 v105, v105, v249
	v_mul_f32_e32 v106, v106, v250
	v_mul_f32_e32 v107, v107, v251
	v_mul_f32_e32 v104, v108, v104
	v_mul_f32_e32 v105, v109, v105
	v_mul_f32_e32 v106, v110, v106
	v_mul_f32_e32 v107, v111, v107
	v_mul_f32_e32 v96, v96, v241
	v_mul_f32_e32 v97, v97, v241
; __device__ __forceinline__ float fsigmoid(float x) { return __builtin_amdgcn_rcpf(1.0f + __builtin_amdgcn_exp2f(-x * LOG2E)); }
; __device__ __forceinline__ u32x4 pack8(f32x4 a, f32x4 b) { u32x4 w; w.x = cvt_pk_bf16(a[0], a[1]); w.y = cvt_pk_bf16(a[2], a[3]); w.z = cvt_pk_bf16(b[0], b[1]); w.w = cvt_pk_bf16(b[2], b[3]); return w; }
; #define ST16(BASE, OFF, VAL) __builtin_amdgcn_raw_buffer_store_b128((VAL), __builtin_amdgcn_make_buffer_rsrc((void*)(BASE), (short)0, 0x7ffffff0, 0x00020000), (int)((unsigned)(OFF) * (unsigned)sizeof(*(BASE))), 0, ST_AUX)
;     __device__ __forceinline__ void operator()(const Acc& acc, const Unit& u, int wr, int wc, int fr, int fq) const {
;     ...
;         for (int ai = 0; ai < 2; ++ai)
; #pragma unroll
;             for (int m = 0; m < 4; ++m) { const unsigned row = rowt + ai * 128 + m * 16; const float rstd = rsqrtf(ss[ai * 4 + m] * (1.0f / 1024.0f) + EPS);
;                 f32x4 h0, h1;
; #pragma unroll
;                 for (int e = 0; e < 4; ++e) { const float g0 = acc[ai][0][m][0][e] * rstd, g1 = acc[ai][0][m][1][e] * rstd;
;                     h0[e] = g0 * fsigmoid(g0) * (acc[ai][1][m][0][e] * rstd); h1[e] = g1 * fsigmoid(g1) * (acc[ai][1][m][1][e] * rstd); }
;                 ST16(HID, (row * DFF + c0), pack8(h0, h1)); }
	v_mul_f32_e32 v98, v98, v241
	v_mul_f32_e32 v99, v99, v241
	v_mul_f32_e32 v100, v100, v241
	v_mul_f32_e32 v101, v101, v241
	v_mul_f32_e32 v102, v102, v241
	v_mul_f32_e32 v103, v103, v241
	v_mul_f32_e32 v248, 0xbfb8aa3b, v96
	v_mul_f32_e32 v249, 0xbfb8aa3b, v97
	v_mul_f32_e32 v250, 0xbfb8aa3b, v98
	v_mul_f32_e32 v251, 0xbfb8aa3b, v99
	v_exp_f32_e32 v248, v248
	v_exp_f32_e32 v249, v249
	v_exp_f32_e32 v250, v250
	v_exp_f32_e32 v251, v251
	v_add_f32_e32 v248, 1.0, v248
	v_add_f32_e32 v249, 1.0, v249
	v_add_f32_e32 v250, 1.0, v250
	v_add_f32_e32 v251, 1.0, v251
	v_rcp_f32_e32 v248, v248
	v_rcp_f32_e32 v249, v249
	v_rcp_f32_e32 v250, v250
	v_rcp_f32_e32 v251, v251
	v_mul_f32_e32 v96, v96, v248
	v_mul_f32_e32 v97, v97, v249
	v_mul_f32_e32 v98, v98, v250
	v_mul_f32_e32 v99, v99, v251
	v_mul_f32_e32 v96, v100, v96
	v_mul_f32_e32 v97, v101, v97
	v_mul_f32_e32 v98, v102, v98
	v_mul_f32_e32 v99, v103, v99
	v_cvt_pk_bf16_f32 v104, v104, v105
	v_cvt_pk_bf16_f32 v105, v106, v107
	v_cvt_pk_bf16_f32 v106, v96, v97
	v_cvt_pk_bf16_f32 v107, v98, v99
	v_add_u32_e32 v154, 0x16000, v136
	buffer_store_dwordx4 v[104:107], v154, s[8:11], 0 offen nt
	v_mul_f32_e32 v88, v88, v242
	v_mul_f32_e32 v89, v89, v242
	v_mul_f32_e32 v90, v90, v242
	v_mul_f32_e32 v91, v91, v242
	v_mul_f32_e32 v92, v92, v242
	v_mul_f32_e32 v93, v93, v242
	v_mul_f32_e32 v94, v94, v242
	v_mul_f32_e32 v95, v95, v242
	v_mul_f32_e32 v248, 0xbfb8aa3b, v88
	v_mul_f32_e32 v249, 0xbfb8aa3b, v89
	v_mul_f32_e32 v250, 0xbfb8aa3b, v90
	v_mul_f32_e32 v251, 0xbfb8aa3b, v91
	v_exp_f32_e32 v248, v248
	v_exp_f32_e32 v249, v249
	v_exp_f32_e32 v250, v250
	v_exp_f32_e32 v251, v251
	v_add_f32_e32 v248, 1.0, v248
	v_add_f32_e32 v249, 1.0, v249
	v_add_f32_e32 v250, 1.0, v250
	v_add_f32_e32 v251, 1.0, v251
	v_rcp_f32_e32 v248, v248
	v_rcp_f32_e32 v249, v249
	v_rcp_f32_e32 v250, v250
	v_rcp_f32_e32 v251, v251
	v_mul_f32_e32 v88, v88, v248
	v_mul_f32_e32 v89, v89, v249
	v_mul_f32_e32 v90, v90, v250
	v_mul_f32_e32 v91, v91, v251
	v_mul_f32_e32 v88, v92, v88
	v_mul_f32_e32 v89, v93, v89
	v_mul_f32_e32 v90, v94, v90
	v_mul_f32_e32 v91, v95, v91
	v_mul_f32_e32 v80, v80, v242
	v_mul_f32_e32 v81, v81, v242
	v_mul_f32_e32 v82, v82, v242
	v_mul_f32_e32 v83, v83, v242
	v_mul_f32_e32 v84, v84, v242
	v_mul_f32_e32 v85, v85, v242
	v_mul_f32_e32 v86, v86, v242
	v_mul_f32_e32 v87, v87, v242
	v_mul_f32_e32 v248, 0xbfb8aa3b, v80
	v_mul_f32_e32 v249, 0xbfb8aa3b, v81
	v_mul_f32_e32 v250, 0xbfb8aa3b, v82
	v_mul_f32_e32 v251, 0xbfb8aa3b, v83
	v_exp_f32_e32 v248, v248
	v_exp_f32_e32 v249, v249
	v_exp_f32_e32 v250, v250
	v_exp_f32_e32 v251, v251
	v_add_f32_e32 v248, 1.0, v248
	v_add_f32_e32 v249, 1.0, v249
	v_add_f32_e32 v250, 1.0, v250
	v_add_f32_e32 v251, 1.0, v251
	v_rcp_f32_e32 v248, v248
	v_rcp_f32_e32 v249, v249
	v_rcp_f32_e32 v250, v250
	v_rcp_f32_e32 v251, v251
	v_mul_f32_e32 v80, v80, v248
	v_mul_f32_e32 v81, v81, v249
	v_mul_f32_e32 v82, v82, v250
	v_mul_f32_e32 v83, v83, v251
	v_mul_f32_e32 v80, v84, v80
	v_mul_f32_e32 v81, v85, v81
	v_mul_f32_e32 v82, v86, v82
	v_mul_f32_e32 v83, v87, v83
	v_cvt_pk_bf16_f32 v88, v88, v89
	v_cvt_pk_bf16_f32 v89, v90, v91
	v_cvt_pk_bf16_f32 v90, v80, v81
	v_cvt_pk_bf16_f32 v91, v82, v83
	v_add_u32_e32 v155, 0x2c000, v136
	buffer_store_dwordx4 v[88:91], v155, s[8:11], 0 offen nt
	v_mul_f32_e32 v72, v72, v243
	v_mul_f32_e32 v73, v73, v243
	v_mul_f32_e32 v74, v74, v243
	v_mul_f32_e32 v75, v75, v243
	v_mul_f32_e32 v76, v76, v243
	v_mul_f32_e32 v77, v77, v243
	v_mul_f32_e32 v78, v78, v243
	v_mul_f32_e32 v79, v79, v243
	v_mul_f32_e32 v248, 0xbfb8aa3b, v72
	v_mul_f32_e32 v249, 0xbfb8aa3b, v73
	v_mul_f32_e32 v250, 0xbfb8aa3b, v74
	v_mul_f32_e32 v251, 0xbfb8aa3b, v75
	v_exp_f32_e32 v248, v248
	v_exp_f32_e32 v249, v249
	v_exp_f32_e32 v250, v250
	v_exp_f32_e32 v251, v251
	v_add_f32_e32 v248, 1.0, v248
	v_add_f32_e32 v249, 1.0, v249
	v_add_f32_e32 v250, 1.0, v250
	v_add_f32_e32 v251, 1.0, v251
	v_rcp_f32_e32 v248, v248
	v_rcp_f32_e32 v249, v249
	v_rcp_f32_e32 v250, v250
	v_rcp_f32_e32 v251, v251
	v_mul_f32_e32 v72, v72, v248
	v_mul_f32_e32 v73, v73, v249
	v_mul_f32_e32 v74, v74, v250
	v_mul_f32_e32 v75, v75, v251
	v_mul_f32_e32 v72, v76, v72
	v_mul_f32_e32 v73, v77, v73
	v_mul_f32_e32 v74, v78, v74
	v_mul_f32_e32 v75, v79, v75
	v_mul_f32_e32 v64, v64, v243
	v_mul_f32_e32 v65, v65, v243
	v_mul_f32_e32 v66, v66, v243
	v_mul_f32_e32 v67, v67, v243
	v_mul_f32_e32 v68, v68, v243
	v_mul_f32_e32 v69, v69, v243
	v_mul_f32_e32 v70, v70, v243
	v_mul_f32_e32 v71, v71, v243
	v_mul_f32_e32 v248, 0xbfb8aa3b, v64
	v_mul_f32_e32 v249, 0xbfb8aa3b, v65
	v_mul_f32_e32 v250, 0xbfb8aa3b, v66
	v_mul_f32_e32 v251, 0xbfb8aa3b, v67
	v_exp_f32_e32 v248, v248
	v_exp_f32_e32 v249, v249
	v_exp_f32_e32 v250, v250
	v_exp_f32_e32 v251, v251
	v_add_f32_e32 v248, 1.0, v248
	v_add_f32_e32 v249, 1.0, v249
	v_add_f32_e32 v250, 1.0, v250
	v_add_f32_e32 v251, 1.0, v251
	v_rcp_f32_e32 v248, v248
	v_rcp_f32_e32 v249, v249
	v_rcp_f32_e32 v250, v250
	v_rcp_f32_e32 v251, v251
	v_mul_f32_e32 v64, v64, v248
	v_mul_f32_e32 v65, v65, v249
	v_mul_f32_e32 v66, v66, v250
	v_mul_f32_e32 v67, v67, v251
	v_mul_f32_e32 v64, v68, v64
	v_mul_f32_e32 v65, v69, v65
	v_mul_f32_e32 v66, v70, v66
	v_mul_f32_e32 v67, v71, v67
	v_cvt_pk_bf16_f32 v72, v72, v73
	v_cvt_pk_bf16_f32 v73, v74, v75
	v_cvt_pk_bf16_f32 v74, v64, v65
	v_cvt_pk_bf16_f32 v75, v66, v67
	v_add_u32_e32 v156, 0x42000, v136
	buffer_store_dwordx4 v[72:75], v156, s[8:11], 0 offen nt
	v_mul_f32_e32 v56, v56, v244
	v_mul_f32_e32 v57, v57, v244
	v_mul_f32_e32 v58, v58, v244
	v_mul_f32_e32 v59, v59, v244
	v_mul_f32_e32 v60, v60, v244
	v_mul_f32_e32 v61, v61, v244
	v_mul_f32_e32 v62, v62, v244
; __device__ __forceinline__ float fsigmoid(float x) { return __builtin_amdgcn_rcpf(1.0f + __builtin_amdgcn_exp2f(-x * LOG2E)); }
; __device__ __forceinline__ u32x4 pack8(f32x4 a, f32x4 b) { u32x4 w; w.x = cvt_pk_bf16(a[0], a[1]); w.y = cvt_pk_bf16(a[2], a[3]); w.z = cvt_pk_bf16(b[0], b[1]); w.w = cvt_pk_bf16(b[2], b[3]); return w; }
; #define ST16(BASE, OFF, VAL) __builtin_amdgcn_raw_buffer_store_b128((VAL), __builtin_amdgcn_make_buffer_rsrc((void*)(BASE), (short)0, 0x7ffffff0, 0x00020000), (int)((unsigned)(OFF) * (unsigned)sizeof(*(BASE))), 0, ST_AUX)
;     __device__ __forceinline__ void operator()(const Acc& acc, const Unit& u, int wr, int wc, int fr, int fq) const {
;     ...
;         for (int ai = 0; ai < 2; ++ai)
; #pragma unroll
;             for (int m = 0; m < 4; ++m) { const unsigned row = rowt + ai * 128 + m * 16; const float rstd = rsqrtf(ss[ai * 4 + m] * (1.0f / 1024.0f) + EPS);
;                 f32x4 h0, h1;
; #pragma unroll
;                 for (int e = 0; e < 4; ++e) { const float g0 = acc[ai][0][m][0][e] * rstd, g1 = acc[ai][0][m][1][e] * rstd;
;                     h0[e] = g0 * fsigmoid(g0) * (acc[ai][1][m][0][e] * rstd); h1[e] = g1 * fsigmoid(g1) * (acc[ai][1][m][1][e] * rstd); }
;                 ST16(HID, (row * DFF + c0), pack8(h0, h1)); }
	v_mul_f32_e32 v63, v63, v244
	v_mul_f32_e32 v248, 0xbfb8aa3b, v56
	v_mul_f32_e32 v249, 0xbfb8aa3b, v57
	v_mul_f32_e32 v250, 0xbfb8aa3b, v58
	v_mul_f32_e32 v251, 0xbfb8aa3b, v59
	v_exp_f32_e32 v248, v248
	v_exp_f32_e32 v249, v249
	v_exp_f32_e32 v250, v250
	v_exp_f32_e32 v251, v251
	v_add_f32_e32 v248, 1.0, v248
	v_add_f32_e32 v249, 1.0, v249
	v_add_f32_e32 v250, 1.0, v250
	v_add_f32_e32 v251, 1.0, v251
	v_rcp_f32_e32 v248, v248
	v_rcp_f32_e32 v249, v249
	v_rcp_f32_e32 v250, v250
	v_rcp_f32_e32 v251, v251
	v_mul_f32_e32 v56, v56, v248
	v_mul_f32_e32 v57, v57, v249
	v_mul_f32_e32 v58, v58, v250
	v_mul_f32_e32 v59, v59, v251
	v_mul_f32_e32 v56, v60, v56
	v_mul_f32_e32 v57, v61, v57
	v_mul_f32_e32 v58, v62, v58
	v_mul_f32_e32 v59, v63, v59
	v_mul_f32_e32 v48, v48, v244
	v_mul_f32_e32 v49, v49, v244
	v_mul_f32_e32 v50, v50, v244
	v_mul_f32_e32 v51, v51, v244
	v_mul_f32_e32 v52, v52, v244
	v_mul_f32_e32 v53, v53, v244
	v_mul_f32_e32 v54, v54, v244
	v_mul_f32_e32 v55, v55, v244
	v_mul_f32_e32 v248, 0xbfb8aa3b, v48
	v_mul_f32_e32 v249, 0xbfb8aa3b, v49
	v_mul_f32_e32 v250, 0xbfb8aa3b, v50
	v_mul_f32_e32 v251, 0xbfb8aa3b, v51
	v_exp_f32_e32 v248, v248
	v_exp_f32_e32 v249, v249
	v_exp_f32_e32 v250, v250
	v_exp_f32_e32 v251, v251
	v_add_f32_e32 v248, 1.0, v248
	v_add_f32_e32 v249, 1.0, v249
	v_add_f32_e32 v250, 1.0, v250
	v_add_f32_e32 v251, 1.0, v251
	v_rcp_f32_e32 v248, v248
	v_rcp_f32_e32 v249, v249
	v_rcp_f32_e32 v250, v250
	v_rcp_f32_e32 v251, v251
	v_mul_f32_e32 v48, v48, v248
	v_mul_f32_e32 v49, v49, v249
	v_mul_f32_e32 v50, v50, v250
	v_mul_f32_e32 v51, v51, v251
	v_mul_f32_e32 v48, v52, v48
	v_mul_f32_e32 v49, v53, v49
	v_mul_f32_e32 v50, v54, v50
	v_mul_f32_e32 v51, v55, v51
	v_cvt_pk_bf16_f32 v56, v56, v57
	v_cvt_pk_bf16_f32 v57, v58, v59
	v_cvt_pk_bf16_f32 v58, v48, v49
	v_cvt_pk_bf16_f32 v59, v50, v51
	v_add_u32_e32 v157, 0xb0000, v136
	buffer_store_dwordx4 v[56:59], v157, s[8:11], 0 offen nt
	v_mul_f32_e32 v40, v40, v245
	v_mul_f32_e32 v41, v41, v245
	v_mul_f32_e32 v42, v42, v245
	v_mul_f32_e32 v43, v43, v245
	v_mul_f32_e32 v44, v44, v245
	v_mul_f32_e32 v45, v45, v245
	v_mul_f32_e32 v46, v46, v245
	v_mul_f32_e32 v47, v47, v245
	v_mul_f32_e32 v248, 0xbfb8aa3b, v40
	v_mul_f32_e32 v249, 0xbfb8aa3b, v41
	v_mul_f32_e32 v250, 0xbfb8aa3b, v42
	v_mul_f32_e32 v251, 0xbfb8aa3b, v43
	v_exp_f32_e32 v248, v248
	v_exp_f32_e32 v249, v249
	v_exp_f32_e32 v250, v250
	v_exp_f32_e32 v251, v251
	v_add_f32_e32 v248, 1.0, v248
	v_add_f32_e32 v249, 1.0, v249
	v_add_f32_e32 v250, 1.0, v250
	v_add_f32_e32 v251, 1.0, v251
	v_rcp_f32_e32 v248, v248
	v_rcp_f32_e32 v249, v249
	v_rcp_f32_e32 v250, v250
	v_rcp_f32_e32 v251, v251
	v_mul_f32_e32 v40, v40, v248
	v_mul_f32_e32 v41, v41, v249
	v_mul_f32_e32 v42, v42, v250
	v_mul_f32_e32 v43, v43, v251
	v_mul_f32_e32 v40, v44, v40
	v_mul_f32_e32 v41, v45, v41
	v_mul_f32_e32 v42, v46, v42
	v_mul_f32_e32 v43, v47, v43
	v_mul_f32_e32 v32, v32, v245
	v_mul_f32_e32 v33, v33, v245
	v_mul_f32_e32 v34, v34, v245
	v_mul_f32_e32 v35, v35, v245
	v_mul_f32_e32 v36, v36, v245
	v_mul_f32_e32 v37, v37, v245
	v_mul_f32_e32 v38, v38, v245
	v_mul_f32_e32 v39, v39, v245
	v_mul_f32_e32 v248, 0xbfb8aa3b, v32
	v_mul_f32_e32 v249, 0xbfb8aa3b, v33
	v_mul_f32_e32 v250, 0xbfb8aa3b, v34
	v_mul_f32_e32 v251, 0xbfb8aa3b, v35
	v_exp_f32_e32 v248, v248
	v_exp_f32_e32 v249, v249
	v_exp_f32_e32 v250, v250
	v_exp_f32_e32 v251, v251
	v_add_f32_e32 v248, 1.0, v248
	v_add_f32_e32 v249, 1.0, v249
	v_add_f32_e32 v250, 1.0, v250
	v_add_f32_e32 v251, 1.0, v251
	v_rcp_f32_e32 v248, v248
	v_rcp_f32_e32 v249, v249
	v_rcp_f32_e32 v250, v250
	v_rcp_f32_e32 v251, v251
	v_mul_f32_e32 v32, v32, v248
	v_mul_f32_e32 v33, v33, v249
	v_mul_f32_e32 v34, v34, v250
	v_mul_f32_e32 v35, v35, v251
	v_mul_f32_e32 v32, v36, v32
	v_mul_f32_e32 v33, v37, v33
	v_mul_f32_e32 v34, v38, v34
	v_mul_f32_e32 v35, v39, v35
	v_cvt_pk_bf16_f32 v40, v40, v41
	v_cvt_pk_bf16_f32 v41, v42, v43
	v_cvt_pk_bf16_f32 v42, v32, v33
	v_cvt_pk_bf16_f32 v43, v34, v35
	v_add_u32_e32 v158, 0xc6000, v136
	buffer_store_dwordx4 v[40:43], v158, s[8:11], 0 offen nt
	v_mul_f32_e32 v24, v24, v246
	v_mul_f32_e32 v25, v25, v246
	v_mul_f32_e32 v26, v26, v246
	v_mul_f32_e32 v27, v27, v246
	v_mul_f32_e32 v28, v28, v246
; __device__ __forceinline__ float fsigmoid(float x) { return __builtin_amdgcn_rcpf(1.0f + __builtin_amdgcn_exp2f(-x * LOG2E)); }
; __device__ __forceinline__ u32x4 pack8(f32x4 a, f32x4 b) { u32x4 w; w.x = cvt_pk_bf16(a[0], a[1]); w.y = cvt_pk_bf16(a[2], a[3]); w.z = cvt_pk_bf16(b[0], b[1]); w.w = cvt_pk_bf16(b[2], b[3]); return w; }
; #define ST16(BASE, OFF, VAL) __builtin_amdgcn_raw_buffer_store_b128((VAL), __builtin_amdgcn_make_buffer_rsrc((void*)(BASE), (short)0, 0x7ffffff0, 0x00020000), (int)((unsigned)(OFF) * (unsigned)sizeof(*(BASE))), 0, ST_AUX)
;     __device__ __forceinline__ void operator()(const Acc& acc, const Unit& u, int wr, int wc, int fr, int fq) const {
;     ...
;         for (int ai = 0; ai < 2; ++ai)
; #pragma unroll
;             for (int m = 0; m < 4; ++m) { const unsigned row = rowt + ai * 128 + m * 16; const float rstd = rsqrtf(ss[ai * 4 + m] * (1.0f / 1024.0f) + EPS);
;                 f32x4 h0, h1;
; #pragma unroll
;                 for (int e = 0; e < 4; ++e) { const float g0 = acc[ai][0][m][0][e] * rstd, g1 = acc[ai][0][m][1][e] * rstd;
;                     h0[e] = g0 * fsigmoid(g0) * (acc[ai][1][m][0][e] * rstd); h1[e] = g1 * fsigmoid(g1) * (acc[ai][1][m][1][e] * rstd); }
;                 ST16(HID, (row * DFF + c0), pack8(h0, h1)); }
	v_mul_f32_e32 v29, v29, v246
	v_mul_f32_e32 v30, v30, v246
	v_mul_f32_e32 v31, v31, v246
	v_mul_f32_e32 v248, 0xbfb8aa3b, v24
	v_mul_f32_e32 v249, 0xbfb8aa3b, v25
	v_mul_f32_e32 v250, 0xbfb8aa3b, v26
	v_mul_f32_e32 v251, 0xbfb8aa3b, v27
	v_exp_f32_e32 v248, v248
	v_exp_f32_e32 v249, v249
	v_exp_f32_e32 v250, v250
	v_exp_f32_e32 v251, v251
	v_add_f32_e32 v248, 1.0, v248
	v_add_f32_e32 v249, 1.0, v249
	v_add_f32_e32 v250, 1.0, v250
	v_add_f32_e32 v251, 1.0, v251
	v_rcp_f32_e32 v248, v248
	v_rcp_f32_e32 v249, v249
	v_rcp_f32_e32 v250, v250
	v_rcp_f32_e32 v251, v251
	v_mul_f32_e32 v24, v24, v248
	v_mul_f32_e32 v25, v25, v249
	v_mul_f32_e32 v26, v26, v250
	v_mul_f32_e32 v27, v27, v251
	v_mul_f32_e32 v24, v28, v24
	v_mul_f32_e32 v25, v29, v25
	v_mul_f32_e32 v26, v30, v26
	v_mul_f32_e32 v27, v31, v27
	v_mul_f32_e32 v16, v16, v246
	v_mul_f32_e32 v17, v17, v246
	v_mul_f32_e32 v18, v18, v246
	v_mul_f32_e32 v19, v19, v246
	v_mul_f32_e32 v20, v20, v246
	v_mul_f32_e32 v21, v21, v246
	v_mul_f32_e32 v22, v22, v246
	v_mul_f32_e32 v23, v23, v246
	v_mul_f32_e32 v248, 0xbfb8aa3b, v16
	v_mul_f32_e32 v249, 0xbfb8aa3b, v17
	v_mul_f32_e32 v250, 0xbfb8aa3b, v18
	v_mul_f32_e32 v251, 0xbfb8aa3b, v19
	v_exp_f32_e32 v248, v248
	v_exp_f32_e32 v249, v249
	v_exp_f32_e32 v250, v250
	v_exp_f32_e32 v251, v251
	v_add_f32_e32 v248, 1.0, v248
	v_add_f32_e32 v249, 1.0, v249
	v_add_f32_e32 v250, 1.0, v250
	v_add_f32_e32 v251, 1.0, v251
	v_rcp_f32_e32 v248, v248
	v_rcp_f32_e32 v249, v249
	v_rcp_f32_e32 v250, v250
	v_rcp_f32_e32 v251, v251
	v_mul_f32_e32 v16, v16, v248
	v_mul_f32_e32 v17, v17, v249
	v_mul_f32_e32 v18, v18, v250
	v_mul_f32_e32 v19, v19, v251
	v_mul_f32_e32 v16, v20, v16
	v_mul_f32_e32 v17, v21, v17
	v_mul_f32_e32 v18, v22, v18
	v_mul_f32_e32 v19, v23, v19
	v_cvt_pk_bf16_f32 v24, v24, v25
	v_cvt_pk_bf16_f32 v25, v26, v27
	v_cvt_pk_bf16_f32 v26, v16, v17
	v_cvt_pk_bf16_f32 v27, v18, v19
	v_add_u32_e32 v159, 0xdc000, v136
	buffer_store_dwordx4 v[24:27], v159, s[8:11], 0 offen nt
	v_mul_f32_e32 v8, v8, v247
	v_mul_f32_e32 v9, v9, v247
	v_mul_f32_e32 v10, v10, v247
	v_mul_f32_e32 v11, v11, v247
	v_mul_f32_e32 v12, v12, v247
	v_mul_f32_e32 v13, v13, v247
	v_mul_f32_e32 v14, v14, v247
	v_mul_f32_e32 v15, v15, v247
	v_mul_f32_e32 v248, 0xbfb8aa3b, v8
	v_mul_f32_e32 v249, 0xbfb8aa3b, v9
	v_mul_f32_e32 v250, 0xbfb8aa3b, v10
	v_mul_f32_e32 v251, 0xbfb8aa3b, v11
	v_exp_f32_e32 v248, v248
	v_exp_f32_e32 v249, v249
	v_exp_f32_e32 v250, v250
	v_exp_f32_e32 v251, v251
	v_add_f32_e32 v248, 1.0, v248
	v_add_f32_e32 v249, 1.0, v249
	v_add_f32_e32 v250, 1.0, v250
	v_add_f32_e32 v251, 1.0, v251
	v_rcp_f32_e32 v248, v248
	v_rcp_f32_e32 v249, v249
	v_rcp_f32_e32 v250, v250
	v_rcp_f32_e32 v251, v251
	v_mul_f32_e32 v8, v8, v248
	v_mul_f32_e32 v9, v9, v249
	v_mul_f32_e32 v10, v10, v250
	v_mul_f32_e32 v11, v11, v251
	v_mul_f32_e32 v8, v12, v8
	v_mul_f32_e32 v9, v13, v9
	v_mul_f32_e32 v10, v14, v10
	v_mul_f32_e32 v11, v15, v11
	v_mul_f32_e32 v4, v4, v247
	v_mul_f32_e32 v5, v5, v247
	v_mul_f32_e32 v6, v6, v247
	v_mul_f32_e32 v7, v7, v247
	v_mul_f32_e32 v0, v0, v247
	v_mul_f32_e32 v1, v1, v247
	v_mul_f32_e32 v2, v2, v247
	v_mul_f32_e32 v3, v3, v247
	v_mul_f32_e32 v248, 0xbfb8aa3b, v4
	v_mul_f32_e32 v249, 0xbfb8aa3b, v5
	v_mul_f32_e32 v250, 0xbfb8aa3b, v6
	v_mul_f32_e32 v251, 0xbfb8aa3b, v7
	v_exp_f32_e32 v248, v248
	v_exp_f32_e32 v249, v249
	v_exp_f32_e32 v250, v250
	v_exp_f32_e32 v251, v251
	v_add_f32_e32 v248, 1.0, v248
	v_add_f32_e32 v249, 1.0, v249
	v_add_f32_e32 v250, 1.0, v250
	v_add_f32_e32 v251, 1.0, v251
	v_rcp_f32_e32 v248, v248
	v_rcp_f32_e32 v249, v249
	v_rcp_f32_e32 v250, v250
	v_rcp_f32_e32 v251, v251
	v_mul_f32_e32 v4, v4, v248
	v_mul_f32_e32 v5, v5, v249
	v_mul_f32_e32 v6, v6, v250
	v_mul_f32_e32 v7, v7, v251
	v_mul_f32_e32 v4, v0, v4
	v_mul_f32_e32 v5, v1, v5
	v_mul_f32_e32 v6, v2, v6
	v_mul_f32_e32 v7, v3, v7
	v_cvt_pk_bf16_f32 v8, v8, v9
	v_cvt_pk_bf16_f32 v9, v10, v11
	v_cvt_pk_bf16_f32 v10, v4, v5
	v_cvt_pk_bf16_f32 v11, v6, v7
	v_add_u32_e32 v160, 0xf2000, v136
	buffer_store_dwordx4 v[8:11], v160, s[8:11], 0 offen nt
	s_andn2_b64 vcc, exec, s[4:5]
	s_mov_b64 s[4:5], -1
	s_cbranch_vccnz .LBB0_1144
	s_andn2_b64 vcc, exec, s[28:29]
	s_cbranch_vccnz .LBB0_1143
	s_barrier
	s_branch .LBB0_1143
